# two more group-local seams (Gates->scan1, scan2->Rout): 10 of 20 seams local; census check now also requires grid==256
# baseline (speedup 1.0000x reference)
; #define LAS __attribute__((address_space(3)))
; __device__ __forceinline__ unsigned xb_add(unsigned* p, unsigned v) { return __hip_atomic_fetch_add(p, v, __ATOMIC_RELAXED, __HIP_MEMORY_SCOPE_AGENT); }
; __device__ __forceinline__ unsigned xb_xcc_id() { return (unsigned)__builtin_amdgcn_s_getreg((3 << 11) | 20) & 0xFu; }
; __global__ void __launch_bounds__(512, 2) mk_fwd(Args args) {
;     ...
;     const int lo = args.ph_lo, hi = args.ph_hi;
;     if (threadIdx.x < 16) ((LAS unsigned*)(lds + 131072))[threadIdx.x] = 0u;
;     if (hi - lo > 1) {
;         if (threadIdx.x == 0) (void)xb_add(&((unsigned*)args.ws)[XB_XCNT(xb_xcc_id())], 1u);
;         cg::this_grid().sync();
;     }
;     __syncthreads();
.LBB0_251:
	s_or_b64 exec, exec, s[2:3]
	s_waitcnt lgkmcnt(0)
	s_barrier
	s_load_dwordx2 s[4:5], s[0:1], 0xf0
	v_mov_b32_e32 v0, 0
	s_waitcnt lgkmcnt(0)
	global_load_dword v1, v0, s[4:5] offset:1088 sc1
	global_load_dword v2, v0, s[4:5] offset:1344 sc1
	global_load_dword v3, v0, s[4:5] offset:1600 sc1
	global_load_dword v4, v0, s[4:5] offset:1856 sc1
	global_load_dword v5, v0, s[4:5] offset:2112 sc1
	global_load_dword v6, v0, s[4:5] offset:2368 sc1
	global_load_dword v7, v0, s[4:5] offset:2624 sc1
	global_load_dword v8, v0, s[4:5] offset:2880 sc1
	s_waitcnt vmcnt(0)
	s_mov_b32 s98, 1
	v_readfirstlane_b32 s6, v1
	s_add_u32 s7, s6, -1
	s_and_b32 s7, s7, s6
	s_cmp_lg_u32 s7, 0
	s_cselect_b32 s98, 0, s98
	s_cmp_eq_u32 s6, 0
	s_cselect_b32 s98, 0, s98
	v_readfirstlane_b32 s6, v2
	s_add_u32 s7, s6, -1
	s_and_b32 s7, s7, s6
	s_cmp_lg_u32 s7, 0
	s_cselect_b32 s98, 0, s98
	s_cmp_eq_u32 s6, 0
	s_cselect_b32 s98, 0, s98
	v_readfirstlane_b32 s6, v3
	s_add_u32 s7, s6, -1
	s_and_b32 s7, s7, s6
	s_cmp_lg_u32 s7, 0
	s_cselect_b32 s98, 0, s98
	s_cmp_eq_u32 s6, 0
	s_cselect_b32 s98, 0, s98
	v_readfirstlane_b32 s6, v4
	s_add_u32 s7, s6, -1
	s_and_b32 s7, s7, s6
	s_cmp_lg_u32 s7, 0
	s_cselect_b32 s98, 0, s98
	s_cmp_eq_u32 s6, 0
	s_cselect_b32 s98, 0, s98
	v_readfirstlane_b32 s6, v5
	s_add_u32 s7, s6, -1
	s_and_b32 s7, s7, s6
	s_cmp_lg_u32 s7, 0
	s_cselect_b32 s98, 0, s98
	s_cmp_eq_u32 s6, 0
	s_cselect_b32 s98, 0, s98
	v_readfirstlane_b32 s6, v6
	s_add_u32 s7, s6, -1
	s_and_b32 s7, s7, s6
	s_cmp_lg_u32 s7, 0
	s_cselect_b32 s98, 0, s98
	s_cmp_eq_u32 s6, 0
	s_cselect_b32 s98, 0, s98
	v_readfirstlane_b32 s6, v7
	s_add_u32 s7, s6, -1
	s_and_b32 s7, s7, s6
	s_cmp_lg_u32 s7, 0
	s_cselect_b32 s98, 0, s98
	s_cmp_eq_u32 s6, 0
	s_cselect_b32 s98, 0, s98
	v_readfirstlane_b32 s6, v8
	s_add_u32 s7, s6, -1
	s_and_b32 s7, s7, s6
	s_cmp_lg_u32 s7, 0
	s_cselect_b32 s98, 0, s98
	s_cmp_eq_u32 s6, 0
	s_cselect_b32 s98, 0, s98
	s_cmpk_lg_u32 s92, 0x100
	s_cselect_b32 s98, 0, s98

; #define LAS __attribute__((address_space(3)))
; __device__ __forceinline__ unsigned xb_ld(unsigned* p)              { return __hip_atomic_load(p, __ATOMIC_RELAXED, __HIP_MEMORY_SCOPE_AGENT); }
; __device__ __forceinline__ unsigned xb_add(unsigned* p, unsigned v) { return __hip_atomic_fetch_add(p, v, __ATOMIC_RELAXED, __HIP_MEMORY_SCOPE_AGENT); }
; __device__ __forceinline__ unsigned xb_xcc_id() { return (unsigned)__builtin_amdgcn_s_getreg((3 << 11) | 20) & 0xFu; }
; #define XB_SPIN(cond, bar) do { unsigned _sp = 0; while (cond) { __builtin_amdgcn_s_sleep(1); \
;     if ((++_sp & 255u) == 0u) { if (xb_ld(&(bar)[XB_TMO])) break; if (_sp > XB_SPIN_CAP) { atomicAdd(&(bar)[XB_TMO], 1u); break; } } } } while (0)
; __device__ __forceinline__ bool is_leader(int wave_s) { int lane; asm volatile("v_mbcnt_lo_u32_b32 %0, -1, 0\n\tv_mbcnt_hi_u32_b32 %0, -1, %0" : "=v"(lane)); return wave_s == 0 && lane == 0; }
; __device__ __forceinline__ void grid_bar(unsigned* bar, volatile LAS unsigned* st, int wave_s, unsigned G) {
;     asm volatile("s_waitcnt vmcnt(0) lgkmcnt(0)" ::: "memory");
;     __syncthreads();
;     if (is_leader(wave_s)) {
;         const unsigned x = xb_xcc_id();
;         unsigned nloc = st[0], nx = st[1];
;         if (nloc == 0u) { xcd_barrier_complete(bar, x, G, nloc, nx); st[0] = nloc; st[1] = nx; }
;         const unsigned old = xb_add(&bar[XB_XSUB(x)], 1u);
;         const unsigned gen = old / nloc;
;         if (old + 1u == (gen + 1u) * nloc) {
;             __builtin_amdgcn_fence(__ATOMIC_RELEASE, "agent");
;             asm volatile("s_waitcnt vmcnt(0)" ::: "memory");
;             const unsigned og = xb_add(&bar[XB_TOP], 1u);
;             const unsigned tg = og / nx;
;             if (og + 1u == (tg + 1u) * nx) xb_add(&bar[XB_TOPGEN], 1u);
;             else XB_SPIN(xb_ld(&bar[XB_TOPGEN]) == tg, bar);
;             __builtin_amdgcn_fence(__ATOMIC_ACQUIRE, "agent");
;             xb_add(&bar[XB_XGEN(x)], 1u);
;             asm volatile("s_waitcnt vmcnt(0)" ::: "memory");
;         } else {
;             XB_SPIN(xb_ld(&bar[XB_XGEN(x)]) == gen, bar);
;             __builtin_amdgcn_fence(__ATOMIC_ACQUIRE, "agent");
;             asm volatile("s_waitcnt vmcnt(0)" ::: "memory");
;         }
;     }
;     __syncthreads();
; }
.LBB0_1532:
	s_mov_b32 s2, s94
	s_mov_b32 s4, s95
	s_cmp_lt_i32 s2, 15
	s_cselect_b64 s[2:3], -1, 0
	s_cmp_gt_i32 s4, 14
	s_cselect_b64 s[4:5], -1, 0
	s_and_b64 s[2:3], s[2:3], s[4:5]
	s_andn2_b64 vcc, exec, s[2:3]
	s_cbranch_vccnz .LBB0_1587
	s_mov_b32 s2, s94
	s_mov_b32 s4, s95
	s_cmp_lt_i32 s2, 16
	s_cselect_b64 s[2:3], -1, 0
	s_cmp_gt_i32 s4, 15
	s_cselect_b64 s[4:5], -1, 0
	s_and_b64 s[2:3], s[2:3], s[4:5]
	s_andn2_b64 vcc, exec, s[2:3]
	s_cbranch_vccnz .LBB0_1587
	s_cmp_lt_u32 s79, 64
	s_waitcnt vmcnt(0) lgkmcnt(0)
	s_cselect_b64 s[2:3], -1, 0
	s_waitcnt vmcnt(0) lgkmcnt(0)
	s_barrier
	v_mbcnt_lo_u32_b32 v0, -1, 0
	v_mbcnt_hi_u32_b32 v0, -1, v0
	s_nop 0
	v_cmp_eq_u32_e32 vcc, 0, v0
	s_and_b64 s[4:5], s[2:3], vcc
	s_and_saveexec_b64 s[2:3], s[4:5]
	s_cbranch_execz .LBB0_1586
	s_cmp_eq_u32 s98, 0
	s_cbranch_scc1 .Lgl_7
	s_load_dwordx2 s[4:5], s[0:1], 0xf0
	s_and_b32 s6, s78, 7
	s_lshl_b32 s6, s6, 8
	s_lshr_b32 s7, s92, 3
	s_mul_i32 s7, s7, 7
	v_mov_b32_e32 v0, s6
	v_mov_b32_e32 v1, 1
	s_waitcnt lgkmcnt(0)
	global_atomic_add v2, v0, v1, s[4:5] offset:1152 sc0
	s_waitcnt vmcnt(0)
	v_readfirstlane_b32 s8, v2
	s_add_i32 s8, s8, 1
	s_cmp_eq_u32 s8, s7
	s_cbranch_scc0 .Lwt_7
	global_atomic_add v0, v1, s[4:5] offset:1216
	s_branch .Lac_7

; #define LAS __attribute__((address_space(3)))
; __device__ __forceinline__ unsigned xb_ld(unsigned* p)              { return __hip_atomic_load(p, __ATOMIC_RELAXED, __HIP_MEMORY_SCOPE_AGENT); }
; __device__ __forceinline__ unsigned xb_add(unsigned* p, unsigned v) { return __hip_atomic_fetch_add(p, v, __ATOMIC_RELAXED, __HIP_MEMORY_SCOPE_AGENT); }
; __device__ __forceinline__ unsigned xb_xcc_id() { return (unsigned)__builtin_amdgcn_s_getreg((3 << 11) | 20) & 0xFu; }
; #define XB_SPIN(cond, bar) do { unsigned _sp = 0; while (cond) { __builtin_amdgcn_s_sleep(1); \
;     if ((++_sp & 255u) == 0u) { if (xb_ld(&(bar)[XB_TMO])) break; if (_sp > XB_SPIN_CAP) { atomicAdd(&(bar)[XB_TMO], 1u); break; } } } } while (0)
; __device__ __forceinline__ bool is_leader(int wave_s) { int lane; asm volatile("v_mbcnt_lo_u32_b32 %0, -1, 0\n\tv_mbcnt_hi_u32_b32 %0, -1, %0" : "=v"(lane)); return wave_s == 0 && lane == 0; }
; __device__ __forceinline__ void grid_bar(unsigned* bar, volatile LAS unsigned* st, int wave_s, unsigned G) {
;     asm volatile("s_waitcnt vmcnt(0) lgkmcnt(0)" ::: "memory");
;     __syncthreads();
;     if (is_leader(wave_s)) {
;         const unsigned x = xb_xcc_id();
;         unsigned nloc = st[0], nx = st[1];
;         if (nloc == 0u) { xcd_barrier_complete(bar, x, G, nloc, nx); st[0] = nloc; st[1] = nx; }
;         const unsigned old = xb_add(&bar[XB_XSUB(x)], 1u);
;         const unsigned gen = old / nloc;
;         if (old + 1u == (gen + 1u) * nloc) {
;             __builtin_amdgcn_fence(__ATOMIC_RELEASE, "agent");
;             asm volatile("s_waitcnt vmcnt(0)" ::: "memory");
;             const unsigned og = xb_add(&bar[XB_TOP], 1u);
;             const unsigned tg = og / nx;
;             if (og + 1u == (tg + 1u) * nx) xb_add(&bar[XB_TOPGEN], 1u);
;             else XB_SPIN(xb_ld(&bar[XB_TOPGEN]) == tg, bar);
;             __builtin_amdgcn_fence(__ATOMIC_ACQUIRE, "agent");
;             xb_add(&bar[XB_XGEN(x)], 1u);
;             asm volatile("s_waitcnt vmcnt(0)" ::: "memory");
;         } else {
;             XB_SPIN(xb_ld(&bar[XB_XGEN(x)]) == gen, bar);
;             __builtin_amdgcn_fence(__ATOMIC_ACQUIRE, "agent");
;             asm volatile("s_waitcnt vmcnt(0)" ::: "memory");
;         }
;     }
;     __syncthreads();
; }
.LBB0_1658:
	s_mov_b32 s2, s94
	s_mov_b32 s4, s95
	s_cmp_lt_i32 s2, 17
	s_cselect_b64 s[2:3], -1, 0
	s_cmp_gt_i32 s4, 16
	s_cselect_b64 s[4:5], -1, 0
	s_and_b64 s[2:3], s[2:3], s[4:5]
	s_andn2_b64 vcc, exec, s[2:3]
	s_cbranch_vccnz .LBB0_1713
	s_mov_b32 s2, s94
	s_mov_b32 s4, s95
	s_cmp_lt_i32 s2, 18
	s_cselect_b64 s[2:3], -1, 0
	s_cmp_gt_i32 s4, 17
	s_cselect_b64 s[4:5], -1, 0
	s_and_b64 s[2:3], s[2:3], s[4:5]
	s_andn2_b64 vcc, exec, s[2:3]
	s_cbranch_vccnz .LBB0_1713
	s_cmp_lt_u32 s79, 64
	s_waitcnt vmcnt(0) lgkmcnt(0)
	s_cselect_b64 s[2:3], -1, 0
	s_waitcnt vmcnt(0) lgkmcnt(0)
	s_barrier
	v_mbcnt_lo_u32_b32 v0, -1, 0
	v_mbcnt_hi_u32_b32 v0, -1, v0
	s_nop 0
	v_cmp_eq_u32_e32 vcc, 0, v0
	s_and_b64 s[4:5], s[2:3], vcc
	s_and_saveexec_b64 s[2:3], s[4:5]
	s_cbranch_execz .LBB0_1712
	s_cmp_eq_u32 s98, 0
	s_cbranch_scc1 .Lgl_8
	s_load_dwordx2 s[4:5], s[0:1], 0xf0
	s_and_b32 s6, s78, 7
	s_lshl_b32 s6, s6, 8
	s_lshr_b32 s7, s92, 3
	s_mul_i32 s7, s7, 8
	v_mov_b32_e32 v0, s6
	v_mov_b32_e32 v1, 1
	s_waitcnt lgkmcnt(0)
	global_atomic_add v2, v0, v1, s[4:5] offset:1152 sc0
	s_waitcnt vmcnt(0)
	v_readfirstlane_b32 s8, v2
	s_add_i32 s8, s8, 1
	s_cmp_eq_u32 s8, s7
	s_cbranch_scc0 .Lwt_8
	global_atomic_add v0, v1, s[4:5] offset:1216
	s_branch .Lac_8

; #define LAS __attribute__((address_space(3)))
; __device__ __forceinline__ unsigned xb_ld(unsigned* p)              { return __hip_atomic_load(p, __ATOMIC_RELAXED, __HIP_MEMORY_SCOPE_AGENT); }
; __device__ __forceinline__ unsigned xb_add(unsigned* p, unsigned v) { return __hip_atomic_fetch_add(p, v, __ATOMIC_RELAXED, __HIP_MEMORY_SCOPE_AGENT); }
; __device__ __forceinline__ unsigned xb_xcc_id() { return (unsigned)__builtin_amdgcn_s_getreg((3 << 11) | 20) & 0xFu; }
; #define XB_SPIN(cond, bar) do { unsigned _sp = 0; while (cond) { __builtin_amdgcn_s_sleep(1); \
;     if ((++_sp & 255u) == 0u) { if (xb_ld(&(bar)[XB_TMO])) break; if (_sp > XB_SPIN_CAP) { atomicAdd(&(bar)[XB_TMO], 1u); break; } } } } while (0)
; __device__ __forceinline__ bool is_leader(int wave_s) { int lane; asm volatile("v_mbcnt_lo_u32_b32 %0, -1, 0\n\tv_mbcnt_hi_u32_b32 %0, -1, %0" : "=v"(lane)); return wave_s == 0 && lane == 0; }
; __device__ __forceinline__ void grid_bar(unsigned* bar, volatile LAS unsigned* st, int wave_s, unsigned G) {
;     asm volatile("s_waitcnt vmcnt(0) lgkmcnt(0)" ::: "memory");
;     __syncthreads();
;     if (is_leader(wave_s)) {
;         const unsigned x = xb_xcc_id();
;         unsigned nloc = st[0], nx = st[1];
;         if (nloc == 0u) { xcd_barrier_complete(bar, x, G, nloc, nx); st[0] = nloc; st[1] = nx; }
;         const unsigned old = xb_add(&bar[XB_XSUB(x)], 1u);
;         const unsigned gen = old / nloc;
;         if (old + 1u == (gen + 1u) * nloc) {
;             __builtin_amdgcn_fence(__ATOMIC_RELEASE, "agent");
;             asm volatile("s_waitcnt vmcnt(0)" ::: "memory");
;             const unsigned og = xb_add(&bar[XB_TOP], 1u);
;             const unsigned tg = og / nx;
;             if (og + 1u == (tg + 1u) * nx) xb_add(&bar[XB_TOPGEN], 1u);
;             else XB_SPIN(xb_ld(&bar[XB_TOPGEN]) == tg, bar);
;             __builtin_amdgcn_fence(__ATOMIC_ACQUIRE, "agent");
;             xb_add(&bar[XB_XGEN(x)], 1u);
;             asm volatile("s_waitcnt vmcnt(0)" ::: "memory");
;         } else {
;             XB_SPIN(xb_ld(&bar[XB_XGEN(x)]) == gen, bar);
;             __builtin_amdgcn_fence(__ATOMIC_ACQUIRE, "agent");
;             asm volatile("s_waitcnt vmcnt(0)" ::: "memory");
;         }
;     }
;     __syncthreads();
; }
.LBB0_1832:
	s_mov_b32 s2, s94
	s_mov_b32 s4, s95
	s_cmp_lt_i32 s2, 19
	s_cselect_b64 s[2:3], -1, 0
	s_cmp_gt_i32 s4, 18
	s_cselect_b64 s[4:5], -1, 0
	s_and_b64 s[2:3], s[2:3], s[4:5]
	s_andn2_b64 vcc, exec, s[2:3]
	s_cbranch_vccnz .LBB0_1887
	s_mov_b32 s2, s94
	s_mov_b32 s4, s95
	s_cmp_lt_i32 s2, 20
	s_cselect_b64 s[2:3], -1, 0
	s_cmp_gt_i32 s4, 19
	s_cselect_b64 s[4:5], -1, 0
	s_and_b64 s[2:3], s[2:3], s[4:5]
	s_andn2_b64 vcc, exec, s[2:3]
	s_cbranch_vccnz .LBB0_1887
	s_cmp_lt_u32 s79, 64
	s_waitcnt vmcnt(0) lgkmcnt(0)
	s_cselect_b64 s[2:3], -1, 0
	s_waitcnt vmcnt(0) lgkmcnt(0)
	s_barrier
	v_mbcnt_lo_u32_b32 v0, -1, 0
	v_mbcnt_hi_u32_b32 v0, -1, v0
	s_nop 0
	v_cmp_eq_u32_e32 vcc, 0, v0
	s_and_b64 s[4:5], s[2:3], vcc
	s_and_saveexec_b64 s[2:3], s[4:5]
	s_cbranch_execz .LBB0_1886
	s_cmp_eq_u32 s98, 0
	s_cbranch_scc1 .Lgl_9
	s_load_dwordx2 s[4:5], s[0:1], 0xf0
	s_and_b32 s6, s78, 7
	s_lshl_b32 s6, s6, 8
	s_lshr_b32 s7, s92, 3
	s_mul_i32 s7, s7, 9
	v_mov_b32_e32 v0, s6
	v_mov_b32_e32 v1, 1
	s_waitcnt lgkmcnt(0)
	global_atomic_add v2, v0, v1, s[4:5] offset:1152 sc0
	s_waitcnt vmcnt(0)
	v_readfirstlane_b32 s8, v2
	s_add_i32 s8, s8, 1
	s_cmp_eq_u32 s8, s7
	s_cbranch_scc0 .Lwt_9
	global_atomic_add v0, v1, s[4:5] offset:1216
	s_branch .Lac_9
.Lwt_9:
	s_sleep 1
	global_load_dword v2, v0, s[4:5] offset:1216 sc1
	s_waitcnt vmcnt(0)
	v_readfirstlane_b32 s8, v2
	s_cmp_lt_u32 s8, 9
	s_cbranch_scc1 .Lwt_9

; #define LAS __attribute__((address_space(3)))
; __device__ __forceinline__ unsigned xb_ld(unsigned* p)              { return __hip_atomic_load(p, __ATOMIC_RELAXED, __HIP_MEMORY_SCOPE_AGENT); }
; __device__ __forceinline__ unsigned xb_add(unsigned* p, unsigned v) { return __hip_atomic_fetch_add(p, v, __ATOMIC_RELAXED, __HIP_MEMORY_SCOPE_AGENT); }
; __device__ __forceinline__ unsigned xb_xcc_id() { return (unsigned)__builtin_amdgcn_s_getreg((3 << 11) | 20) & 0xFu; }
; #define XB_SPIN(cond, bar) do { unsigned _sp = 0; while (cond) { __builtin_amdgcn_s_sleep(1); \
;     if ((++_sp & 255u) == 0u) { if (xb_ld(&(bar)[XB_TMO])) break; if (_sp > XB_SPIN_CAP) { atomicAdd(&(bar)[XB_TMO], 1u); break; } } } } while (0)
; __device__ __forceinline__ bool is_leader(int wave_s) { int lane; asm volatile("v_mbcnt_lo_u32_b32 %0, -1, 0\n\tv_mbcnt_hi_u32_b32 %0, -1, %0" : "=v"(lane)); return wave_s == 0 && lane == 0; }
; __device__ __forceinline__ void grid_bar(unsigned* bar, volatile LAS unsigned* st, int wave_s, unsigned G) {
;     asm volatile("s_waitcnt vmcnt(0) lgkmcnt(0)" ::: "memory");
;     __syncthreads();
;     if (is_leader(wave_s)) {
;         const unsigned x = xb_xcc_id();
;         unsigned nloc = st[0], nx = st[1];
;         if (nloc == 0u) { xcd_barrier_complete(bar, x, G, nloc, nx); st[0] = nloc; st[1] = nx; }
;         const unsigned old = xb_add(&bar[XB_XSUB(x)], 1u);
;         const unsigned gen = old / nloc;
;         if (old + 1u == (gen + 1u) * nloc) {
;             __builtin_amdgcn_fence(__ATOMIC_RELEASE, "agent");
;             asm volatile("s_waitcnt vmcnt(0)" ::: "memory");
;             const unsigned og = xb_add(&bar[XB_TOP], 1u);
;             const unsigned tg = og / nx;
;             if (og + 1u == (tg + 1u) * nx) xb_add(&bar[XB_TOPGEN], 1u);
;             else XB_SPIN(xb_ld(&bar[XB_TOPGEN]) == tg, bar);
;             __builtin_amdgcn_fence(__ATOMIC_ACQUIRE, "agent");
;             xb_add(&bar[XB_XGEN(x)], 1u);
;             asm volatile("s_waitcnt vmcnt(0)" ::: "memory");
;         } else {
;             XB_SPIN(xb_ld(&bar[XB_XGEN(x)]) == gen, bar);
;             __builtin_amdgcn_fence(__ATOMIC_ACQUIRE, "agent");
;             asm volatile("s_waitcnt vmcnt(0)" ::: "memory");
;         }
;     }
;     __syncthreads();
; }
.LBB0_1962:
	s_mov_b32 s2, s94
	s_mov_b32 s4, s95
	s_cmp_lt_i32 s2, 20
	s_cselect_b64 s[2:3], -1, 0
	s_cmp_gt_i32 s4, 19
	s_cselect_b64 s[4:5], -1, 0
	s_and_b64 s[2:3], s[2:3], s[4:5]
	s_andn2_b64 vcc, exec, s[2:3]
	s_cbranch_vccnz .LBB0_2017
	s_mov_b32 s2, s94
	s_mov_b32 s4, s95
	s_cmp_lt_i32 s2, 21
	s_cselect_b64 s[2:3], -1, 0
	s_cmp_gt_i32 s4, 20
	s_cselect_b64 s[4:5], -1, 0
	s_and_b64 s[2:3], s[2:3], s[4:5]
	s_andn2_b64 vcc, exec, s[2:3]
	s_cbranch_vccnz .LBB0_2017
	s_cmp_lt_u32 s79, 64
	s_waitcnt vmcnt(0) lgkmcnt(0)
	s_cselect_b64 s[2:3], -1, 0
	s_waitcnt vmcnt(0) lgkmcnt(0)
	s_barrier
	v_mbcnt_lo_u32_b32 v0, -1, 0
	v_mbcnt_hi_u32_b32 v0, -1, v0
	s_nop 0
	v_cmp_eq_u32_e32 vcc, 0, v0
	s_and_b64 s[4:5], s[2:3], vcc
	s_and_saveexec_b64 s[2:3], s[4:5]
	s_cbranch_execz .LBB0_2016
	s_cmp_eq_u32 s98, 0
	s_cbranch_scc1 .Lgl_10
	s_load_dwordx2 s[4:5], s[0:1], 0xf0
	s_and_b32 s6, s78, 7
	s_lshl_b32 s6, s6, 8
	s_lshr_b32 s7, s92, 3
	s_mul_i32 s7, s7, 10
	v_mov_b32_e32 v0, s6
	v_mov_b32_e32 v1, 1
	s_waitcnt lgkmcnt(0)
	global_atomic_add v2, v0, v1, s[4:5] offset:1152 sc0
	s_waitcnt vmcnt(0)
	v_readfirstlane_b32 s8, v2
	s_add_i32 s8, s8, 1
	s_cmp_eq_u32 s8, s7
	s_cbranch_scc0 .Lwt_10
	global_atomic_add v0, v1, s[4:5] offset:1216
	s_branch .Lac_10
.Lwt_10:
	s_sleep 1
	global_load_dword v2, v0, s[4:5] offset:1216 sc1
	s_waitcnt vmcnt(0)
	v_readfirstlane_b32 s8, v2
	s_cmp_lt_u32 s8, 10
	s_cbranch_scc1 .Lwt_10
